# fill_rstd_table: one-load-per-unit cache warm-up pass before the serialized per-unit reduction (3 GEMM phases), on top of v36
# speedup vs baseline: 1.0097x; 1.0036x over previous
; #define LAS __attribute__((address_space(3)))
; __device__ __forceinline__ void fill_rstd_table(LAS float* RT, const float* SSQP, const pg8::Order& S, int tid) {
;     pg8::Unit uu;
;     for (int i = 0; S.next(i, uu); ++i) {
;         if (tid < 256) {
;             const f32x4* pp = (const f32x4*)(SSQP + (size_t)(uu.pm * 256 + tid) * 32);
;             float sacc = 0.f;
; #pragma unroll
;             for (int q = 0; q < 8; ++q) { const f32x4 v = pp[q]; sacc += (v[0] + v[1]) + (v[2] + v[3]); }
;             RT[i * 256 + tid] = 1.0f / sqrtf(sacc * (1.0f / DM) + 1e-6f);
;         }
;     }
.Lpf0_638:
	s_or_b64 exec, exec, s[6:7]
	s_add_i32 s9, s9, 1
	s_mov_b64 s[6:7], 0

;     __device__ bool next(int i, Unit& u) const {
;         const long L = (long)i * G + c; if (L >= (long)per * nZ) return false;
.Lpf0_640:
	s_mul_i32 s4, s9, s8
	s_mul_hi_u32 s5, s9, s94
	s_add_i32 s5, s5, s4
	s_mul_i32 s4, s9, s94
	s_add_u32 s4, s4, s2
	s_addc_u32 s5, s5, s3
	v_cmp_gt_i64_e32 vcc, s[4:5], v[0:1]
	s_mov_b64 s[6:7], -1
	s_cbranch_vccnz .Lpf0_639

;     __device__ bool next(int i, Unit& u) const {
;     ...
;         int wgid = (int)L; { const int q = nwg / NXCD, r = nwg % NXCD, xcd = wgid % NXCD, off = wgid / NXCD; wgid = (xcd < r ? xcd * (q + 1) : r * (q + 1) + (xcd - r) * q) + off; }
	s_ashr_i32 s5, s4, 31
	s_lshr_b32 s5, s5, 29
	s_add_i32 s11, s4, s5
	s_and_b32 s5, s11, -8
	s_sub_i32 s6, s4, s5
	s_cmp_gt_i32 s6, -1
	s_mov_b64 s[4:5], -1

;     __device__ bool next(int i, Unit& u) const {
;     ...
;         int wgid = (int)L; { const int q = nwg / NXCD, r = nwg % NXCD, xcd = wgid % NXCD, off = wgid / NXCD; wgid = (xcd < r ? xcd * (q + 1) : r * (q + 1) + (xcd - r) * q) + off; }
	s_cbranch_scc1 .Lpf0_644

;     __device__ bool next(int i, Unit& u) const {
;     ...
;         int wgid = (int)L; { const int q = nwg / NXCD, r = nwg % NXCD, xcd = wgid % NXCD, off = wgid / NXCD; wgid = (xcd < r ? xcd * (q + 1) : r * (q + 1) + (xcd - r) * q) + off; }
	s_andn2_b64 vcc, exec, s[4:5]
	s_cbranch_vccz .Lpf0_645

;     __device__ bool next(int i, Unit& u) const {
;     ...
;         int wgid = (int)L; { const int q = nwg / NXCD, r = nwg % NXCD, xcd = wgid % NXCD, off = wgid / NXCD; wgid = (xcd < r ? xcd * (q + 1) : r * (q + 1) + (xcd - r) * q) + off; }
;         u.z = wgid / per; wgid -= u.z * per;
;         const int nig = WGM * nN, gid = wgid / nig, fm = gid * WGM, gsz = (nM - fm) < WGM ? (nM - fm) : WGM;
;         u.pm = fm + ((wgid % nig) % gsz); u.pn = (wgid % nig) / gsz; u.i = i; return true;
; __device__ __forceinline__ void fill_rstd_table(LAS float* RT, const float* SSQP, const pg8::Order& S, int tid) {
;     ...
;             const f32x4* pp = (const f32x4*)(SSQP + (size_t)(uu.pm * 256 + tid) * 32);
.Lpf0_646:
	s_ashr_i32 s4, s11, 3
	s_add_i32 s4, s12, s4
	s_ashr_i32 s5, s4, 31
	s_lshr_b32 s5, s5, 21
	s_add_i32 s5, s4, s5
	s_and_b32 s5, s5, 0xf800
	s_sub_i32 s4, s4, s5
	s_sext_i32_i16 s5, s4
	s_bfe_u32 s5, s5, 0x70018
	s_add_i32 s5, s4, s5
	s_sext_i32_i16 s11, s5
	s_and_b32 s5, s5, 0xff80
	s_sub_i32 s4, s4, s5
	s_bfe_i32 s5, s4, 0x80000
	s_bfe_u32 s5, s5, 0x2000d
	s_add_i32 s5, s4, s5
	s_and_b32 s5, s5, 0xfc
	s_sub_i32 s4, s4, s5
	s_sext_i32_i8 s4, s4
	s_lshl_b32 s5, s11, 3
	s_and_b32 s5, s5, 0xfffffc00
	s_lshl_b32 s4, s4, 8
	s_add_i32 s4, s4, s5
	v_add_u32_e32 v6, s4, v2
	v_ashrrev_i32_e32 v7, 31, v6
	v_lshlrev_b64 v[6:7], 7, v[6:7]
	v_lshl_add_u64 v[6:7], s[24:25], 0, v[6:7]
	global_load_dword v250, v[6:7], off
	s_branch .Lpf0_638
.Lpf0_done:
	s_mov_b32 s9, 0
	s_branch .LBB0_640

;     __device__ bool next(int i, Unit& u) const {
;         const long L = (long)i * G + c; if (L >= (long)per * nZ) return false;
.Lpf1_736:
	s_mul_i32 s4, s9, s8
	s_mul_hi_u32 s5, s9, s94
	s_add_i32 s5, s5, s4
	s_mul_i32 s4, s9, s94
	s_add_u32 s4, s4, s2
	s_addc_u32 s5, s5, s3
	v_cmp_gt_i64_e32 vcc, s[4:5], v[0:1]
	s_mov_b64 s[6:7], -1
	s_cbranch_vccnz .Lpf1_735

; __device__ __forceinline__ void fill_rstd_table(LAS float* RT, const float* SSQP, const pg8::Order& S, int tid) {
;     ...
;         if (tid < 256) {
	s_and_saveexec_b64 s[6:7], s[0:1]
	s_cbranch_execz .Lpf1_734

;     __device__ bool next(int i, Unit& u) const {
;     ...
;         int wgid = (int)L; { const int q = nwg / NXCD, r = nwg % NXCD, xcd = wgid % NXCD, off = wgid / NXCD; wgid = (xcd < r ? xcd * (q + 1) : r * (q + 1) + (xcd - r) * q) + off; }
;         u.z = wgid / per; wgid -= u.z * per;
;         const int nig = WGM * nN, gid = wgid / nig, fm = gid * WGM, gsz = (nM - fm) < WGM ? (nM - fm) : WGM;
;         u.pm = fm + ((wgid % nig) % gsz); u.pn = (wgid % nig) / gsz; u.i = i; return true;
; __device__ __forceinline__ void fill_rstd_table(LAS float* RT, const float* SSQP, const pg8::Order& S, int tid) {
;     ...
;             const f32x4* pp = (const f32x4*)(SSQP + (size_t)(uu.pm * 256 + tid) * 32);
	s_ashr_i32 s5, s4, 31
	s_lshr_b32 s5, s5, 29
	s_add_i32 s5, s4, s5
	s_ashr_i32 s12, s5, 3
	s_and_b32 s5, s5, -8
	s_sub_i32 s4, s4, s5
	s_cmp_lt_i32 s4, 0
	s_cselect_b32 s5, s10, 0xc0
	s_mul_i32 s4, s4, s5
	s_add_i32 s4, s4, s12
	s_mul_hi_i32 s5, s4, 0x2aaaaaab
	s_lshr_b32 s12, s5, 31
	s_lshr_b32 s5, s5, 8
	s_add_i32 s5, s5, s12
	s_mulk_i32 s5, 0x600
	s_sub_i32 s4, s4, s5
	s_sext_i32_i16 s5, s4
	s_mulk_i32 s5, 0x2aab
	s_lshr_b32 s12, s5, 31
	s_ashr_i32 s5, s5, 20
	s_add_i32 s5, s5, s12
	s_mul_i32 s12, s5, 0x60
	s_sub_i32 s4, s4, s12
	s_bfe_i32 s12, s4, 0x80000
	s_bfe_u32 s12, s12, 0x2000d
	s_add_i32 s12, s4, s12
	s_and_b32 s12, s12, 0xfc
	s_sub_i32 s4, s4, s12
	s_sext_i32_i8 s4, s4
	s_lshl_b32 s5, s5, 10
	s_lshl_b32 s4, s4, 8
	s_add_i32 s4, s4, s5
	v_add_u32_e32 v6, s4, v2
	v_ashrrev_i32_e32 v7, 31, v6
	v_lshlrev_b64 v[6:7], 7, v[6:7]
	v_lshl_add_u64 v[6:7], s[24:25], 0, v[6:7]
	global_load_dword v250, v[6:7], off
	s_branch .Lpf1_734
